# v21 plus MLA attention row-max via v_permlane16/32_swap instead of ds_bpermute
# speedup vs baseline: 1.0092x; 1.0032x over previous
; DI f32x4 mfma16(bf16x8 a, bf16x8 b, f32x4 c) { return __builtin_amdgcn_mfma_f32_16x16x32_bf16(a, b, c, 0, 0, 0); }
; DI float fexp2(float x) { return __builtin_amdgcn_exp2f(x); }
; template <int KS, bool MASK, int NC, bool SH>
; DI void attn_block(const u16* Qp, int qstride, const u16* Kp, int kstride, const u16* Vtp, const u64* maskp, int nkt_w, int nkt_max,
;                    const u16* gatep, int gstride, u16* outp, int ostride, char* lds, int tid) {
;     ...
; #pragma unroll
;     for (int a = 0; a < 4; ++a)
; #pragma unroll
;       for (int ks = 0; ks < KS; ++ks) {
;         const bf16x8 kf = *reinterpret_cast<const bf16x8*>(kb + ((16 * a + jn) * KROW + ks * 32 + q * 8) * 2);
; #pragma unroll
;         for (int c = 0; c < NC; ++c) s[a][c] = mfma16(kf, qf[c][ks], s[a][c]);
;       }
;     if (MASK) {
; #pragma unroll
;       for (int c = 0; c < NC; ++c) {
;         const u64 w = ((SH || c == 0) ? w0 : w1) >> (4 * q);
; #pragma unroll
;         for (int a = 0; a < 4; ++a)
; #pragma unroll
;           for (int r = 0; r < 4; ++r)
;             if (!((w >> (16 * a + r)) & 1ull)) s[a][c][r] = NEG_INF;
;       }
;     }
;     float alpha[NC];
; #pragma unroll
;     for (int c = 0; c < NC; ++c) {
;       float mx = NEG_INF;
; #pragma unroll
;       for (int a = 0; a < 4; ++a)
; #pragma unroll
;         for (int r = 0; r < 4; ++r) mx = fmaxf(mx, s[a][c][r]);
;       mx = fmaxf(mx, __shfl_xor(mx, 16)); mx = fmaxf(mx, __shfl_xor(mx, 32));
;       const float mn = fmaxf(m[c], mx);
;       const float mu = (mn == NEG_INF) ? 0.f : mn;
;       alpha[c] = fexp2(m[c] - mu);
;       m[c] = mn;
;       float ps = 0.f;
; #pragma unroll
;       for (int a = 0; a < 4; ++a)
; #pragma unroll
;         for (int r = 0; r < 4; ++r) { float p = fexp2(s[a][c][r] - mu); s[a][c][r] = p; ps += p; }
;       lsum[c] = lsum[c] * alpha[c] + ps;
;     }
;     bool resc = false;
; #pragma unroll
;     for (int c = 0; c < NC; ++c) resc = resc || (alpha[c] != 1.0f);
;     if (__builtin_amdgcn_ballot_w64(resc) != 0ull) {
; #pragma unroll
;       for (int c = 0; c < NC; ++c)
; #pragma unroll
;         for (int dt = 0; dt < 4; ++dt)
; #pragma unroll
;           for (int r = 0; r < 4; ++r) o[dt][c][r] *= alpha[c];
;     }
.LBB0_768:
	s_cmp_gt_i32 s12, s9
	s_cbranch_scc1 .LBB0_772
	ds_read_b128 v[98:101], v173
	ds_read_b128 v[106:109], v173 offset:64
	v_and_b32_e32 v168, 64, v166
	v_xor_b32_e32 v0, 16, v166
	v_add_u32_e32 v168, 64, v168
	v_cmp_lt_i32_e32 vcc, v0, v168
	s_waitcnt vmcnt(10) lgkmcnt(1)
	v_mfma_f32_16x16x32_bf16 v[102:105], v[98:101], v[34:37], 0
	v_cndmask_b32_e32 v0, v166, v0, vcc
	v_lshlrev_b32_e32 v169, 2, v0
	v_xor_b32_e32 v0, 32, v166
	s_waitcnt vmcnt(6)
	v_mfma_f32_16x16x32_bf16 v[98:101], v[98:101], v[50:53], 0
	ds_read_b128 v[114:117], v173 offset:3392
	v_cmp_lt_i32_e32 vcc, v0, v168
	ds_read_b128 v[122:125], v173 offset:6720
	s_waitcnt lgkmcnt(2)
	v_mfma_f32_16x16x32_bf16 v[102:105], v[106:109], v[38:41], v[102:105]
	v_cndmask_b32_e32 v0, v166, v0, vcc
	v_lshlrev_b32_e32 v168, 2, v0
	ds_read_b128 v[126:129], v173 offset:6784
	v_mfma_f32_16x16x32_bf16 v[98:101], v[106:109], v[46:49], v[98:101]
	ds_read_b128 v[106:109], v173 offset:128
	ds_read_b128 v[176:179], v173 offset:10048
	s_waitcnt lgkmcnt(1)
	v_mfma_f32_16x16x32_bf16 v[110:113], v[106:109], v[42:45], v[102:105]
	s_nop 2
	ds_read_b128 v[102:105], v173 offset:3328
	s_nop 3
	v_max3_f32 v0, v110, s33, v111
	s_waitcnt vmcnt(5)
	v_mfma_f32_16x16x32_bf16 v[98:101], v[106:109], v[54:57], v[98:101]
	v_max3_f32 v0, v0, v112, v113
	s_waitcnt lgkmcnt(0)
	v_mfma_f32_16x16x32_bf16 v[106:109], v[102:105], v[34:37], 0
	v_mfma_f32_16x16x32_bf16 v[102:105], v[102:105], v[50:53], 0
	v_mfma_f32_16x16x32_bf16 v[106:109], v[114:117], v[38:41], v[106:109]
	v_mfma_f32_16x16x32_bf16 v[102:105], v[114:117], v[46:49], v[102:105]
	ds_read_b128 v[114:117], v173 offset:3456
	s_waitcnt lgkmcnt(0)
	v_mfma_f32_16x16x32_bf16 v[118:121], v[114:117], v[42:45], v[106:109]
	s_nop 3
	ds_read_b128 v[106:109], v173 offset:6656
	s_nop 2
	v_max3_f32 v0, v0, v118, v119
	v_mfma_f32_16x16x32_bf16 v[102:105], v[114:117], v[54:57], v[102:105]
	v_max3_f32 v0, v0, v120, v121
	s_waitcnt lgkmcnt(0)
	v_mfma_f32_16x16x32_bf16 v[114:117], v[106:109], v[34:37], 0
	v_mfma_f32_16x16x32_bf16 v[106:109], v[106:109], v[50:53], 0
	v_mfma_f32_16x16x32_bf16 v[114:117], v[122:125], v[38:41], v[114:117]
	v_mfma_f32_16x16x32_bf16 v[106:109], v[122:125], v[46:49], v[106:109]
	v_mfma_f32_16x16x32_bf16 v[122:125], v[126:129], v[42:45], v[114:117]
	s_nop 5
	ds_read_b128 v[114:117], v173 offset:9984
	v_mfma_f32_16x16x32_bf16 v[106:109], v[126:129], v[54:57], v[106:109]
	v_max3_f32 v0, v0, v122, v123
	v_max3_f32 v0, v0, v124, v125
	s_waitcnt lgkmcnt(0)
	v_mfma_f32_16x16x32_bf16 v[126:129], v[114:117], v[34:37], 0
	v_mfma_f32_16x16x32_bf16 v[114:117], v[114:117], v[50:53], 0
	v_mfma_f32_16x16x32_bf16 v[126:129], v[176:179], v[38:41], v[126:129]
	v_mfma_f32_16x16x32_bf16 v[114:117], v[176:179], v[46:49], v[114:117]
	ds_read_b128 v[176:179], v173 offset:10112
	s_waitcnt lgkmcnt(0)
	v_mfma_f32_16x16x32_bf16 v[126:129], v[176:179], v[42:45], v[126:129]
	s_nop 7
	v_max3_f32 v0, v0, v126, v127
	v_max3_f32 v0, v0, v128, v129
	v_mov_b32_e32 v175, v0
	s_nop 1
	v_permlane16_swap_b32_e32 v175, v0
	v_mfma_f32_16x16x32_bf16 v[114:117], v[176:179], v[54:57], v[114:117]
	s_waitcnt lgkmcnt(0)
	v_max_f32_e32 v175, v175, v175
	v_max_f32_e32 v0, v0, v175
	v_mov_b32_e32 v175, v0
	s_nop 1
	v_permlane32_swap_b32_e32 v175, v0
	s_waitcnt lgkmcnt(0)
	v_max3_f32 v0, v157, v0, v175
	v_max3_f32 v175, v98, s33, v99
	v_max3_f32 v175, v175, v100, v101
	v_max3_f32 v175, v175, v102, v103
	v_max3_f32 v175, v175, v104, v105
	v_max3_f32 v175, v175, v106, v107
	v_max3_f32 v175, v175, v108, v109
	v_max3_f32 v175, v175, v114, v115
	v_max3_f32 v175, v175, v116, v117
	v_mov_b32_e32 v169, v175
	s_nop 1
	v_permlane16_swap_b32_e32 v169, v175
	v_cmp_neq_f32_e32 vcc, s33, v0
	s_waitcnt lgkmcnt(0)
	v_max_f32_e32 v169, v169, v169
	v_max_f32_e32 v169, v175, v169
	v_mov_b32_e32 v168, v169
	s_nop 1
	v_permlane32_swap_b32_e32 v168, v169
	v_cndmask_b32_e32 v176, 0, v0, vcc
	v_sub_f32_e32 v157, v157, v176
	v_exp_f32_e32 v157, v157
	s_waitcnt lgkmcnt(0)
	v_max3_f32 v175, v156, v169, v168
	v_cmp_neq_f32_e32 vcc, s33, v175
	s_nop 1
	v_cndmask_b32_e32 v177, 0, v175, vcc
	v_sub_f32_e32 v156, v156, v177
	v_exp_f32_e32 v156, v156
	v_cmp_neq_f32_e32 vcc, 1.0, v157
	v_cmp_neq_f32_e64 s[0:1], 1.0, v156
	s_or_b64 vcc, vcc, s[0:1]
	s_cbranch_vccz .LBB0_771
	v_mov_b32_e32 v178, v157
	v_pk_mul_f32 v[96:97], v[96:97], v[178:179] op_sel_hi:[1,0]
	v_pk_mul_f32 v[94:95], v[94:95], v[178:179] op_sel_hi:[1,0]
	v_pk_mul_f32 v[68:69], v[68:69], v[178:179] op_sel_hi:[1,0]
	v_pk_mul_f32 v[66:67], v[66:67], v[178:179] op_sel_hi:[1,0]
	v_pk_mul_f32 v[24:25], v[24:25], v[178:179] op_sel_hi:[1,0]
	v_pk_mul_f32 v[22:23], v[22:23], v[178:179] op_sel_hi:[1,0]
	v_pk_mul_f32 v[20:21], v[20:21], v[178:179] op_sel_hi:[1,0]
	v_pk_mul_f32 v[18:19], v[18:19], v[178:179] op_sel_hi:[1,0]
	v_pk_mul_f32 v[14:15], v[14:15], v[156:157] op_sel_hi:[1,0]
	v_pk_mul_f32 v[16:17], v[16:17], v[156:157] op_sel_hi:[1,0]
	v_pk_mul_f32 v[10:11], v[10:11], v[156:157] op_sel_hi:[1,0]
	v_pk_mul_f32 v[12:13], v[12:13], v[156:157] op_sel_hi:[1,0]
	v_pk_mul_f32 v[6:7], v[6:7], v[156:157] op_sel_hi:[1,0]
	v_pk_mul_f32 v[8:9], v[8:9], v[156:157] op_sel_hi:[1,0]
	v_pk_mul_f32 v[2:3], v[2:3], v[156:157] op_sel_hi:[1,0]
	v_pk_mul_f32 v[4:5], v[4:5], v[156:157] op_sel_hi:[1,0]

; DI f32x4 mfma16(bf16x8 a, bf16x8 b, f32x4 c) { return __builtin_amdgcn_mfma_f32_16x16x32_bf16(a, b, c, 0, 0, 0); }
; DI float fexp2(float x) { return __builtin_amdgcn_exp2f(x); }
; template <int KS, bool MASK, int NC, bool SH>
; DI void attn_block(const u16* Qp, int qstride, const u16* Kp, int kstride, const u16* Vtp, const u64* maskp, int nkt_w, int nkt_max,
;                    const u16* gatep, int gstride, u16* outp, int ostride, char* lds, int tid) {
;     ...
; #pragma unroll
;     for (int a = 0; a < 4; ++a)
; #pragma unroll
;       for (int ks = 0; ks < KS; ++ks) {
;         const bf16x8 kf = *reinterpret_cast<const bf16x8*>(kb + ((16 * a + jn) * KROW + ks * 32 + q * 8) * 2);
; #pragma unroll
;         for (int c = 0; c < NC; ++c) s[a][c] = mfma16(kf, qf[c][ks], s[a][c]);
;       }
;     if (MASK) {
; #pragma unroll
;       for (int c = 0; c < NC; ++c) {
;         const u64 w = ((SH || c == 0) ? w0 : w1) >> (4 * q);
; #pragma unroll
;         for (int a = 0; a < 4; ++a)
; #pragma unroll
;           for (int r = 0; r < 4; ++r)
;             if (!((w >> (16 * a + r)) & 1ull)) s[a][c][r] = NEG_INF;
;       }
;     }
;     float alpha[NC];
; #pragma unroll
;     for (int c = 0; c < NC; ++c) {
;       float mx = NEG_INF;
; #pragma unroll
;       for (int a = 0; a < 4; ++a)
; #pragma unroll
;         for (int r = 0; r < 4; ++r) mx = fmaxf(mx, s[a][c][r]);
;       mx = fmaxf(mx, __shfl_xor(mx, 16)); mx = fmaxf(mx, __shfl_xor(mx, 32));
;       const float mn = fmaxf(m[c], mx);
;       const float mu = (mn == NEG_INF) ? 0.f : mn;
;       alpha[c] = fexp2(m[c] - mu);
;       m[c] = mn;
;       float ps = 0.f;
; #pragma unroll
;       for (int a = 0; a < 4; ++a)
; #pragma unroll
;         for (int r = 0; r < 4; ++r) { float p = fexp2(s[a][c][r] - mu); s[a][c][r] = p; ps += p; }
;       lsum[c] = lsum[c] * alpha[c] + ps;
;     }
;     bool resc = false;
; #pragma unroll
;     for (int c = 0; c < NC; ++c) resc = resc || (alpha[c] != 1.0f);
;     if (__builtin_amdgcn_ballot_w64(resc) != 0ull) {
; #pragma unroll
;       for (int c = 0; c < NC; ++c)
; #pragma unroll
;         for (int dt = 0; dt < 4; ++dt)
; #pragma unroll
;           for (int r = 0; r < 4; ++r) o[dt][c][r] *= alpha[c];
;     }
.LBB0_775:
	s_cmp_ge_i32 s12, s9
	s_cbranch_scc1 .LBB0_779
	ds_read_b128 v[98:101], v173 offset:22528
	ds_read_b128 v[106:109], v173 offset:22592
	s_waitcnt lgkmcnt(1)
	v_mfma_f32_16x16x32_bf16 v[102:105], v[98:101], v[34:37], 0
	ds_read_b128 v[110:113], v173 offset:25920
	ds_read_b128 v[122:125], v173 offset:29248
	ds_read_b128 v[126:129], v173 offset:29312
	v_mfma_f32_16x16x32_bf16 v[98:101], v[98:101], v[50:53], 0
	ds_read_b128 v[146:149], v173 offset:32576
	s_waitcnt lgkmcnt(4)
	v_mfma_f32_16x16x32_bf16 v[102:105], v[106:109], v[38:41], v[102:105]
	v_mfma_f32_16x16x32_bf16 v[98:101], v[106:109], v[46:49], v[98:101]
	ds_read_b128 v[106:109], v173 offset:22656
	s_waitcnt lgkmcnt(0)
	v_mfma_f32_16x16x32_bf16 v[114:117], v[106:109], v[42:45], v[102:105]
	v_mfma_f32_16x16x32_bf16 v[106:109], v[106:109], v[54:57], v[98:101]
	s_nop 3
	ds_read_b128 v[98:101], v173 offset:25856
	s_waitcnt lgkmcnt(0)
	v_mfma_f32_16x16x32_bf16 v[102:105], v[98:101], v[34:37], 0
	v_mfma_f32_16x16x32_bf16 v[98:101], v[98:101], v[50:53], 0
	v_mfma_f32_16x16x32_bf16 v[102:105], v[110:113], v[38:41], v[102:105]
	v_mfma_f32_16x16x32_bf16 v[98:101], v[110:113], v[46:49], v[98:101]
	ds_read_b128 v[110:113], v173 offset:25984
	s_waitcnt lgkmcnt(0)
	v_mfma_f32_16x16x32_bf16 v[118:121], v[110:113], v[42:45], v[102:105]
	s_nop 3
	ds_read_b128 v[102:105], v173 offset:29184
	v_mfma_f32_16x16x32_bf16 v[98:101], v[110:113], v[54:57], v[98:101]
	s_waitcnt lgkmcnt(0)
	v_mfma_f32_16x16x32_bf16 v[110:113], v[102:105], v[34:37], 0
	v_mfma_f32_16x16x32_bf16 v[102:105], v[102:105], v[50:53], 0
	v_mfma_f32_16x16x32_bf16 v[110:113], v[122:125], v[38:41], v[110:113]
	v_mfma_f32_16x16x32_bf16 v[102:105], v[122:125], v[46:49], v[102:105]
	v_mfma_f32_16x16x32_bf16 v[122:125], v[126:129], v[42:45], v[110:113]
	s_nop 5
	ds_read_b128 v[110:113], v173 offset:32512
	v_mfma_f32_16x16x32_bf16 v[102:105], v[126:129], v[54:57], v[102:105]
	s_waitcnt lgkmcnt(0)
	v_mfma_f32_16x16x32_bf16 v[126:129], v[110:113], v[34:37], 0
	v_mfma_f32_16x16x32_bf16 v[110:113], v[110:113], v[50:53], 0
	v_mfma_f32_16x16x32_bf16 v[126:129], v[146:149], v[38:41], v[126:129]
	v_mfma_f32_16x16x32_bf16 v[110:113], v[146:149], v[46:49], v[110:113]
	ds_read_b128 v[146:149], v173 offset:32640
	s_waitcnt lgkmcnt(0)
	v_mfma_f32_16x16x32_bf16 v[126:129], v[146:149], v[42:45], v[126:129]
	v_mfma_f32_16x16x32_bf16 v[110:113], v[146:149], v[54:57], v[110:113]
	v_and_b32_e32 v147, 64, v166
	v_xor_b32_e32 v146, 16, v166
	v_add_u32_e32 v147, 64, v147
	v_cmp_lt_i32_e32 vcc, v146, v147
	v_xor_b32_e32 v148, 32, v166
	s_nop 0
	v_cndmask_b32_e32 v146, v166, v146, vcc
	v_cmp_lt_i32_e32 vcc, v148, v147
	v_lshlrev_b32_e32 v146, 2, v146
	s_nop 0
	v_cndmask_b32_e32 v147, v166, v148, vcc
	v_lshlrev_b32_e32 v149, 2, v147
	v_max3_f32 v147, v114, s33, v115
	v_max3_f32 v147, v147, v116, v117
	v_max3_f32 v147, v147, v118, v119
	v_max3_f32 v147, v147, v120, v121
	v_max3_f32 v147, v147, v122, v123
	v_max3_f32 v147, v147, v124, v125
	v_max3_f32 v147, v147, v126, v127
	v_max3_f32 v147, v147, v128, v129
	v_mov_b32_e32 v148, v147
	s_nop 1
	v_permlane16_swap_b32_e32 v148, v147
	s_waitcnt lgkmcnt(0)
	v_max_f32_e32 v148, v148, v148
	v_max_f32_e32 v147, v147, v148
	v_mov_b32_e32 v148, v147
	s_nop 1
	v_permlane32_swap_b32_e32 v148, v147
	s_waitcnt lgkmcnt(0)
	v_max3_f32 v157, v0, v147, v148
	v_cmp_neq_f32_e32 vcc, s33, v157
	s_nop 1
	v_cndmask_b32_e32 v148, 0, v157, vcc
	v_sub_f32_e32 v0, v0, v148
	v_exp_f32_e32 v147, v0
	v_max3_f32 v0, v106, s33, v107
	v_max3_f32 v0, v0, v108, v109
	v_max3_f32 v0, v0, v98, v99
	v_max3_f32 v0, v0, v100, v101
	v_max3_f32 v0, v0, v102, v103
	v_max3_f32 v0, v0, v104, v105
	v_max3_f32 v0, v0, v110, v111
	v_max3_f32 v0, v0, v112, v113
	v_mov_b32_e32 v146, v0
	s_nop 1
	v_permlane16_swap_b32_e32 v146, v0
	s_waitcnt lgkmcnt(0)
	v_max_f32_e32 v146, v146, v146
	v_max_f32_e32 v0, v0, v146
	v_mov_b32_e32 v146, v0
	s_nop 1
	v_permlane32_swap_b32_e32 v146, v0
	s_waitcnt lgkmcnt(0)
	v_max3_f32 v156, v175, v0, v146
	v_cmp_neq_f32_e32 vcc, s33, v156
	s_nop 1
	v_cndmask_b32_e32 v0, 0, v156, vcc
	v_sub_f32_e32 v146, v175, v0
	v_exp_f32_e32 v146, v146
	v_cmp_neq_f32_e32 vcc, 1.0, v147
	v_cmp_neq_f32_e64 s[0:1], 1.0, v146
	s_or_b64 vcc, vcc, s[0:1]
	s_cbranch_vccz .LBB0_778
	v_mov_b32_e32 v150, v147
	v_pk_mul_f32 v[96:97], v[96:97], v[150:151] op_sel_hi:[1,0]
	v_pk_mul_f32 v[94:95], v[94:95], v[150:151] op_sel_hi:[1,0]
	v_pk_mul_f32 v[68:69], v[68:69], v[150:151] op_sel_hi:[1,0]
	v_pk_mul_f32 v[66:67], v[66:67], v[150:151] op_sel_hi:[1,0]
	v_pk_mul_f32 v[24:25], v[24:25], v[150:151] op_sel_hi:[1,0]
	v_pk_mul_f32 v[22:23], v[22:23], v[150:151] op_sel_hi:[1,0]
	v_pk_mul_f32 v[20:21], v[20:21], v[150:151] op_sel_hi:[1,0]
	v_pk_mul_f32 v[18:19], v[18:19], v[150:151] op_sel_hi:[1,0]
	v_pk_mul_f32 v[14:15], v[14:15], v[146:147] op_sel_hi:[1,0]
	v_pk_mul_f32 v[16:17], v[16:17], v[146:147] op_sel_hi:[1,0]
	v_pk_mul_f32 v[10:11], v[10:11], v[146:147] op_sel_hi:[1,0]
	v_pk_mul_f32 v[12:13], v[12:13], v[146:147] op_sel_hi:[1,0]
	v_pk_mul_f32 v[6:7], v[6:7], v[146:147] op_sel_hi:[1,0]
	v_pk_mul_f32 v[8:9], v[8:9], v[146:147] op_sel_hi:[1,0]
	v_pk_mul_f32 v[2:3], v[2:3], v[146:147] op_sel_hi:[1,0]
	v_pk_mul_f32 v[4:5], v[4:5], v[146:147] op_sel_hi:[1,0]
